# flag wave-wide + x-row L2 prefetch + params.ws reload removed + cmp2 loop software-pipelined (global loads, counted vmcnt)
# speedup vs baseline: 1.0007x; 1.0007x over previous
.LBB0_66:
	s_movk_i32 s8, 0x7fff
	s_cmpk_gt_i32 s52, 0x7fff
	v_mbcnt_lo_u32_b32 v228, -1, 0
	s_cbranch_scc1 .LBB0_69
	v_mbcnt_hi_u32_b32 v2, -1, v228
	v_and_b32_e32 v1, 64, v2
	v_add_u32_e32 v3, 64, v1
	v_xor_b32_e32 v1, 1, v2
	v_cmp_lt_i32_e32 vcc, v1, v3
	v_xor_b32_e32 v4, 2, v2
	s_ashr_i32 s53, s52, 31
	v_cndmask_b32_e32 v1, v2, v1, vcc
	v_cmp_lt_i32_e32 vcc, v4, v3
	s_load_dwordx2 s[2:3], s[0:1], 0x0
	s_lshl_b64 s[4:5], s[52:53], 11
	v_cndmask_b32_e32 v4, v2, v4, vcc
	v_lshlrev_b32_e32 v6, 2, v4
	v_xor_b32_e32 v4, 4, v2
	v_cmp_lt_i32_e32 vcc, v4, v3
	s_add_u32 s4, s44, s4
	v_mov_b32_e32 v5, 0
	v_cndmask_b32_e32 v4, v2, v4, vcc
	v_lshlrev_b32_e32 v7, 2, v4
	v_xor_b32_e32 v4, 8, v2
	v_cmp_lt_i32_e32 vcc, v4, v3
	s_addc_u32 s5, s45, s5
	s_ashr_i32 s55, s54, 31
	v_cndmask_b32_e32 v4, v2, v4, vcc
	v_lshlrev_b32_e32 v8, 2, v4
	v_xor_b32_e32 v4, 16, v2
	v_cmp_lt_i32_e32 vcc, v4, v3
	s_lshl_b64 s[6:7], s[52:53], 12
	v_lshlrev_b32_e32 v1, 2, v1
	v_cndmask_b32_e32 v4, v2, v4, vcc
	v_lshlrev_b32_e32 v9, 2, v4
	v_xor_b32_e32 v4, 32, v2
	v_cmp_lt_i32_e32 vcc, v4, v3
	v_mov_b32_e32 v11, 0x358637bd
	s_mov_b32 s9, 0xf800000
	v_cndmask_b32_e32 v2, v2, v4, vcc
	v_lshlrev_b32_e32 v4, 3, v229
	v_lshlrev_b32_e32 v10, 2, v2
	v_lshl_add_u64 v[2:3], s[4:5], 0, v[4:5]
	s_mov_b64 s[4:5], 0x5000000
	v_lshl_add_u64 v[2:3], v[2:3], 0, s[4:5]
	s_lshl_b64 s[4:5], s[54:55], 11
	s_waitcnt lgkmcnt(0)
	s_add_u32 s2, s2, s6
	v_lshlrev_b32_e32 v4, 4, v229
	s_addc_u32 s3, s3, s7
	v_lshl_add_u64 v[4:5], s[2:3], 0, v[4:5]
	s_mov_b64 s[2:3], 0xc00
	v_lshl_add_u64 v[4:5], v[4:5], 0, s[2:3]
	s_lshl_b64 s[6:7], s[54:55], 12
	v_mov_b32_e32 v12, 0x260
	s_mov_b32 s12, 0xffff0000
	s_mov_b32 s13, s52
	s_sub_u32 s60, 0, s6
	s_subb_u32 s61, 0, s7
	v_mul_u32_u24_e32 v246, 48, v229
	v_add_u32_e32 v246, 0xfffff400, v246
	v_mov_b32_e32 v247, -1
.LBB0_68:
	global_load_dwordx4 v[14:17], v[4:5], off offset:-3072
	global_load_dwordx4 v[18:21], v[4:5], off offset:-2048
	global_load_dwordx4 v[22:25], v[4:5], off offset:-1024
	global_load_dwordx4 v[26:29], v[4:5], off
	s_add_i32 s13, s13, s54
	v_lshl_add_u64 v[4:5], v[4:5], 0, s[6:7]
	s_cmp_lt_i32 s13, 0x8000
	s_cselect_b32 s72, 0, s60
	s_cselect_b32 s73, 0, s61
	v_lshl_add_u64 v[248:249], v[4:5], 0, s[72:73]
	v_lshl_add_u64 v[248:249], v[248:249], 0, v[246:247]
	global_load_dword v250, v[248:249], off
	s_waitcnt vmcnt(4)
	v_mul_f32_e32 v13, v15, v15
	v_mul_f32_e32 v30, v17, v17
	s_waitcnt vmcnt(3)
	v_mul_f32_e32 v31, v19, v19
	v_mul_f32_e32 v32, v21, v21
	s_waitcnt vmcnt(2)
	v_mul_f32_e32 v33, v23, v23
	v_mul_f32_e32 v34, v25, v25
	v_fmac_f32_e32 v13, v14, v14
	v_fmac_f32_e32 v30, v16, v16
	v_fmac_f32_e32 v31, v18, v18
	v_fmac_f32_e32 v32, v20, v20
	s_waitcnt vmcnt(1)
	v_mul_f32_e32 v35, v27, v27
	v_mul_f32_e32 v36, v29, v29
	v_fmac_f32_e32 v33, v22, v22
	v_fmac_f32_e32 v34, v24, v24
	v_add_f32_e32 v13, v13, v30
	v_add_f32_e32 v30, v31, v32
	v_fmac_f32_e32 v35, v26, v26
	v_fmac_f32_e32 v36, v28, v28
	v_add_f32_e32 v31, v33, v34
	v_add_f32_e32 v13, v13, v30
	v_add_f32_e32 v32, v35, v36
	v_add_f32_e32 v13, v13, v31
	v_add_f32_e32 v13, v13, v32
	ds_bpermute_b32 v30, v1, v13
	s_waitcnt lgkmcnt(0)
	v_add_f32_e32 v13, v13, v30
	ds_bpermute_b32 v30, v6, v13
	s_waitcnt lgkmcnt(0)
	v_add_f32_e32 v13, v13, v30
	ds_bpermute_b32 v30, v7, v13
	s_waitcnt lgkmcnt(0)
	v_add_f32_e32 v13, v13, v30
	ds_bpermute_b32 v30, v8, v13
	s_waitcnt lgkmcnt(0)
	v_add_f32_e32 v13, v13, v30
	ds_bpermute_b32 v30, v9, v13
	s_waitcnt lgkmcnt(0)
	v_add_f32_e32 v13, v13, v30
	ds_bpermute_b32 v30, v10, v13
	s_waitcnt lgkmcnt(0)
	v_add_f32_e32 v13, v13, v30
	v_fmamk_f32 v13, v13, 0x3a800000, v11
	v_mul_f32_e32 v30, 0x4f800000, v13
	v_cmp_gt_f32_e32 vcc, s9, v13
	s_nop 1
	v_cndmask_b32_e32 v13, v13, v30, vcc
	v_sqrt_f32_e32 v30, v13
	s_nop 0
	v_add_u32_e32 v31, -1, v30
	v_add_u32_e32 v32, 1, v30
	v_fma_f32 v33, -v31, v30, v13
	v_fma_f32 v34, -v32, v30, v13
	v_cmp_ge_f32_e64 s[2:3], 0, v33
	s_nop 1
	v_cndmask_b32_e64 v30, v30, v31, s[2:3]
	v_cmp_lt_f32_e64 s[2:3], 0, v34
	s_nop 1
	v_cndmask_b32_e64 v30, v30, v32, s[2:3]
	v_mul_f32_e32 v31, 0x37800000, v30
	v_cndmask_b32_e32 v30, v30, v31, vcc
	v_cmp_class_f32_e32 vcc, v13, v12
	s_nop 1
	v_cndmask_b32_e32 v13, v30, v13, vcc
	v_div_scale_f32 v30, s[2:3], v13, v13, 1.0
	v_rcp_f32_e32 v32, v30
	v_div_scale_f32 v31, vcc, 1.0, v13, 1.0
	v_fma_f32 v33, -v30, v32, 1.0
	v_fmac_f32_e32 v32, v33, v32
	v_mul_f32_e32 v33, v31, v32
	v_fma_f32 v34, -v30, v33, v31
	v_fmac_f32_e32 v33, v34, v32
	v_fma_f32 v30, -v30, v33, v31
	v_div_fmas_f32 v30, v30, v32, v33
	v_div_fixup_f32 v13, v30, v13, 1.0
	v_mul_f32_e32 v14, v14, v13
	v_mul_f32_e32 v16, v16, v13
	v_mul_f32_e32 v15, v15, v13
	v_mul_f32_e32 v17, v17, v13
	v_mul_f32_e32 v18, v18, v13
	v_mul_f32_e32 v19, v19, v13
	v_mul_f32_e32 v20, v20, v13
	v_mul_f32_e32 v21, v21, v13
	v_mul_f32_e32 v22, v22, v13
	v_mul_f32_e32 v23, v23, v13
	v_mul_f32_e32 v24, v24, v13
	v_mul_f32_e32 v25, v25, v13
	v_mul_f32_e32 v26, v26, v13
	v_mul_f32_e32 v27, v27, v13
	v_mul_f32_e32 v28, v28, v13
	v_mul_f32_e32 v13, v29, v13
	v_bfe_u32 v29, v14, 16, 1
	v_bfe_u32 v31, v16, 16, 1
	v_bfe_u32 v30, v15, 16, 1
	v_bfe_u32 v32, v17, 16, 1
	v_bfe_u32 v33, v18, 16, 1
	v_bfe_u32 v35, v20, 16, 1
	v_bfe_u32 v37, v22, 16, 1
	v_bfe_u32 v39, v24, 16, 1
	v_bfe_u32 v41, v26, 16, 1
	v_bfe_u32 v43, v28, 16, 1
	v_add3_u32 v14, v14, v29, s8
	v_add3_u32 v16, v16, v31, s8
	v_bfe_u32 v34, v19, 16, 1
	v_bfe_u32 v36, v21, 16, 1
	v_bfe_u32 v38, v23, 16, 1
	v_bfe_u32 v40, v25, 16, 1
	v_bfe_u32 v42, v27, 16, 1
	v_bfe_u32 v44, v13, 16, 1
	v_add3_u32 v15, v15, v30, s8
	v_add3_u32 v17, v17, v32, s8
	v_add3_u32 v18, v18, v33, s8
	v_add3_u32 v20, v20, v35, s8
	v_add3_u32 v22, v22, v37, s8
	v_add3_u32 v24, v24, v39, s8
	v_add3_u32 v26, v26, v41, s8
	v_add3_u32 v28, v28, v43, s8
	v_lshrrev_b32_e32 v14, 16, v14
	v_lshrrev_b32_e32 v16, 16, v16
	v_add3_u32 v19, v19, v34, s8
	v_add3_u32 v21, v21, v36, s8
	v_add3_u32 v23, v23, v38, s8
	v_add3_u32 v25, v25, v40, s8
	v_add3_u32 v27, v27, v42, s8
	v_add3_u32 v13, v13, v44, s8
	v_lshrrev_b32_e32 v18, 16, v18
	v_lshrrev_b32_e32 v20, 16, v20
	v_lshrrev_b32_e32 v22, 16, v22
	v_lshrrev_b32_e32 v24, 16, v24
	v_lshrrev_b32_e32 v26, 16, v26
	v_lshrrev_b32_e32 v28, 16, v28
	v_and_or_b32 v14, v15, s12, v14
	v_and_or_b32 v15, v17, s12, v16
	v_and_or_b32 v16, v19, s12, v18
	v_and_or_b32 v17, v21, s12, v20
	v_and_or_b32 v18, v23, s12, v22
	v_and_or_b32 v19, v25, s12, v24
	v_and_or_b32 v20, v27, s12, v26
	v_and_or_b32 v21, v13, s12, v28
	global_store_dwordx2 v[2:3], v[14:15], off
	global_store_dwordx2 v[2:3], v[16:17], off offset:512
	global_store_dwordx2 v[2:3], v[18:19], off offset:1024
	global_store_dwordx2 v[2:3], v[20:21], off offset:1536
	v_lshl_add_u64 v[2:3], v[2:3], 0, s[4:5]
	s_cbranch_scc1 .LBB0_68

.LBB0_369:
	s_or_b64 exec, exec, s[0:1]
	s_cmpk_lt_i32 s46, 0x50
	s_mov_b64 s[0:1], -1
	s_waitcnt lgkmcnt(0)
	s_barrier
	s_cbranch_scc0 .LBB0_484
	s_cmpk_gt_i32 s52, 0x28ff
	s_cbranch_scc1 .LBB0_441
	s_waitcnt vmcnt(0)
	v_mov_b32_e32 v49, 0
	v_mov_b32_e32 v12, s44
	v_mov_b32_e32 v13, s45
	s_add_u32 s0, s44, 0x3308018
	v_mov_b32_e32 v16, 0x3308000
	s_addc_u32 s1, s45, 0
	global_load_dwordx2 v[14:15], v16, s[44:45] offset:16
	global_load_dwordx4 v[0:3], v16, s[44:45] offset:152
	global_load_dwordx4 v[4:7], v16, s[44:45] offset:24
	global_load_dwordx2 v[50:51], v16, s[44:45] offset:88
	global_load_dwordx4 v[8:11], v16, s[44:45] offset:176
	global_load_dwordx2 v[52:53], v49, s[0:1] offset:16
	s_mul_i32 s8, s85, 0x2200
	v_lshlrev_b32_e32 v48, 4, v176
	v_mul_u32_u24_e32 v16, 0x420, v176
	v_lshlrev_b32_e32 v17, 2, v174
	s_add_i32 s8, s8, 0
	s_mov_b64 s[4:5], 0x2f00000
	v_or_b32_e32 v76, 32, v174
	s_mov_b64 s[14:15], 0x2900000
	s_mov_b64 s[0:1], 0x1700000
	s_mov_b64 s[2:3], 0x700000
	s_mov_b64 s[60:61], 0x500000
	s_mov_b64 s[62:63], 0x1000
	s_lshl_b32 s33, s52, 1
	v_add3_u32 v82, s8, v16, v17
	s_mov_b32 s9, 0
	v_lshlrev_b32_e32 v55, 2, v176
	v_mul_u32_u24_e32 v72, 0x84, v174
	v_or_b32_e32 v73, 8, v174
	v_or_b32_e32 v74, 16, v174
	v_or_b32_e32 v75, 24, v174
	v_lshlrev_b32_e32 v54, 3, v176
	v_or_b32_e32 v77, 40, v174
	v_or_b32_e32 v78, 48, v174
	v_or_b32_e32 v79, 56, v174
	s_mov_b32 s16, 0x8000
	s_mov_b32 s17, 0x10000
	s_mov_b32 s20, 0x18000
	s_mov_b32 s21, 0x20000
	s_mov_b32 s22, 0x28000
	s_mov_b32 s23, 0x30000
	s_mov_b32 s24, 0x38000
	s_movk_i32 s25, 0x7fff
	s_mov_b32 s26, 0xffff0000
	s_mov_b32 s27, 0xe000
	s_mov_b32 s28, 0x1c000
	s_mov_b32 s29, 0x2a000
	s_mov_b32 s30, 0x46000
	s_mov_b32 s31, 0x54000
	s_mov_b32 s34, 0x62000
	s_movk_i32 s35, 0x400
	s_mov_b32 s36, 0x40000
	s_mov_b32 s37, 0x60000
	s_mov_b32 s38, 0x80000
	v_mul_u32_u24_e32 v80, 0x84, v76
	s_lshl_b32 s39, s52, 5
	s_lshl_b32 s40, s54, 5
	s_lshl_b32 s41, s54, 1
	v_add_u32_e32 v81, s8, v48
	s_add_i32 s53, s33, 0x1b100
	s_mov_b32 s55, s52
	s_waitcnt vmcnt(5)
	v_lshl_add_u64 v[60:61], v[14:15], 0, s[62:63]
	v_lshl_add_u64 v[16:17], v[12:13], 0, v[48:49]
	v_lshl_add_u64 v[56:57], v[12:13], 0, s[0:1]
	v_lshl_add_u64 v[58:59], v[12:13], 0, s[2:3]
	s_waitcnt vmcnt(4)
	v_cmp_ne_u64_e64 s[0:1], 0, v[0:1]
	s_waitcnt vmcnt(3)
	v_cmp_ne_u64_e64 s[2:3], 0, v[4:5]
	v_lshl_add_u64 v[62:63], v[16:17], 0, s[4:5]
	v_lshl_add_u64 v[64:65], v[16:17], 0, s[14:15]
	v_lshl_add_u64 v[66:67], v[16:17], 0, s[60:61]
	s_branch .LBB0_374

.LBB0_484:
	s_and_b64 vcc, exec, s[0:1]
	s_cbranch_vccz .LBB0_593
	s_cmp_gt_i32 s18, 47
	s_mov_b64 s[0:1], -1
	s_cbranch_scc0 .LBB0_568
	s_cmpk_gt_u32 s18, 0x4f
	s_cbranch_scc0 .LBB0_559
	s_add_i32 s16, s52, 0xfffffd80
	s_cmpk_gt_i32 s16, 0x28ff
	s_cbranch_scc1 .LBB0_558
	s_waitcnt vmcnt(0)
	v_mov_b32_e32 v49, 0
	v_mov_b32_e32 v12, s44
	v_mov_b32_e32 v13, s45
	s_add_u32 s0, s44, 0x3308018
	v_mov_b32_e32 v16, 0x3308000
	s_addc_u32 s1, s45, 0
	global_load_dwordx2 v[14:15], v16, s[44:45] offset:16
	global_load_dwordx4 v[0:3], v16, s[44:45] offset:152
	global_load_dwordx4 v[4:7], v16, s[44:45] offset:24
	global_load_dwordx2 v[50:51], v16, s[44:45] offset:88
	global_load_dwordx4 v[8:11], v16, s[44:45] offset:176
	global_load_dwordx2 v[52:53], v49, s[0:1] offset:16
	s_mul_i32 s8, s85, 0x2200
	v_lshlrev_b32_e32 v48, 4, v176
	v_mul_u32_u24_e32 v16, 0x420, v176
	v_lshlrev_b32_e32 v17, 2, v174
	s_add_i32 s8, s8, 0
	s_mov_b64 s[4:5], 0x2f00000
	v_or_b32_e32 v76, 32, v174
	s_mov_b64 s[14:15], 0x2900000
	s_mov_b64 s[0:1], 0x1700000
	s_mov_b64 s[2:3], 0x700000
	s_mov_b64 s[60:61], 0x500000
	s_mov_b64 s[62:63], 0x1000
	s_add_i32 s39, s54, 0xfffffd80
	s_lshl_b32 s33, s16, 1
	v_add3_u32 v82, s8, v16, v17
	s_mov_b32 s9, 0
	v_lshlrev_b32_e32 v55, 2, v176
	v_mul_u32_u24_e32 v72, 0x84, v174
	v_or_b32_e32 v73, 8, v174
	v_or_b32_e32 v74, 16, v174
	v_or_b32_e32 v75, 24, v174
	v_lshlrev_b32_e32 v54, 3, v176
	v_or_b32_e32 v77, 40, v174
	v_or_b32_e32 v78, 48, v174
	v_or_b32_e32 v79, 56, v174
	s_mov_b32 s17, 0x8000
	s_mov_b32 s20, 0x10000
	s_mov_b32 s21, 0x18000
	s_mov_b32 s22, 0x20000
	s_mov_b32 s23, 0x28000
	s_mov_b32 s24, 0x30000
	s_mov_b32 s25, 0x38000
	s_movk_i32 s26, 0x7fff
	s_mov_b32 s27, 0xffff0000
	s_mov_b32 s28, 0xe000
	s_mov_b32 s29, 0x1c000
	s_mov_b32 s30, 0x2a000
	s_mov_b32 s31, 0x46000
	s_mov_b32 s34, 0x54000
	s_mov_b32 s35, 0x62000
	s_movk_i32 s36, 0x400
	s_mov_b32 s37, 0x40000
	s_mov_b32 s38, 0x60000
	v_mul_u32_u24_e32 v80, 0x84, v76
	s_lshl_b32 s40, s16, 5
	v_add_u32_e32 v81, s8, v48
	s_lshl_b32 s41, s39, 5
	s_add_i32 s53, s33, 0x1b100
	s_lshl_b32 s55, s39, 1
	s_waitcnt vmcnt(5)
	v_lshl_add_u64 v[60:61], v[14:15], 0, s[62:63]
	v_lshl_add_u64 v[16:17], v[12:13], 0, v[48:49]
	v_lshl_add_u64 v[56:57], v[12:13], 0, s[0:1]
	v_lshl_add_u64 v[58:59], v[12:13], 0, s[2:3]
	s_waitcnt vmcnt(4)
	v_cmp_ne_u64_e64 s[0:1], 0, v[0:1]
	s_waitcnt vmcnt(3)
	v_cmp_ne_u64_e64 s[2:3], 0, v[4:5]
	v_lshl_add_u64 v[62:63], v[16:17], 0, s[4:5]
	v_lshl_add_u64 v[64:65], v[16:17], 0, s[14:15]
	v_lshl_add_u64 v[66:67], v[16:17], 0, s[60:61]
	s_mov_b32 s60, 0x80000
	s_branch .LBB0_491

.LBB0_645:
	s_or_b64 exec, exec, s[0:1]
	v_mov_b32_e32 v7, 0
	s_waitcnt lgkmcnt(0)
	s_barrier
	v_mov_b32_e32 v0, s44
	v_mov_b32_e32 v1, s45
	v_mov_b32_e32 v6, 0x3308000
	global_load_dwordx2 v[4:5], v6, s[44:45] offset:72
	s_cmpk_gt_i32 s52, 0x2fcf
	v_lshrrev_b32_e32 v230, 5, v229
	s_waitcnt vmcnt(1)
	v_readfirstlane_b32 s4, v0
	v_readfirstlane_b32 s5, v1
	s_cbranch_scc1 .LBB0_661
	global_load_dwordx4 v[0:3], v6, s[44:45] offset:136
	global_load_dwordx2 v[12:13], v7, s[6:7]
	s_add_u32 s16, s4, 0x3f00000
	s_addc_u32 s21, s5, 0
	v_lshlrev_b32_e32 v6, 2, v229
	s_add_u32 s22, s4, 0x4600000
	v_lshlrev_b32_e32 v8, 9, v230
	v_lshlrev_b32_e32 v9, 3, v229
	s_movk_i32 s14, 0x3d07
	v_lshlrev_b32_e32 v10, 5, v229
	v_mbcnt_hi_u32_b32 v22, -1, v228
	s_addc_u32 s23, s5, 0
	s_mov_b64 s[2:3], 0x3400000
	v_or3_b32 v8, v8, v9, s14
	v_and_b32_e32 v23, 0x700, v10
	v_or_b32_e32 v10, 0x38f8, v10
	v_and_b32_e32 v9, 64, v22
	s_add_u32 s24, s4, 0x4500000
	v_cmp_lt_u32_e64 s[0:1], 31, v229
	s_mov_b64 s[6:7], 0x1000
	s_movk_i32 s17, 0x7fff
	v_mov_b32_e32 v20, 0x358637bd
	s_mov_b32 s20, 0xf800000
	v_mov_b32_e32 v21, 0x260
	s_mov_b64 s[8:9], 0x1f00
	v_xor_b32_e32 v24, 1, v22
	v_xor_b32_e32 v25, 2, v22
	v_lshlrev_b32_e32 v8, 1, v8
	v_lshlrev_b32_e32 v10, 1, v10
	v_add_u32_e32 v26, 64, v9
	s_addc_u32 s25, s5, 0
	s_mov_b32 s26, s52
	s_waitcnt vmcnt(1)
	v_lshl_add_u64 v[0:1], v[0:1], 0, v[6:7]
	s_waitcnt vmcnt(0)
	v_lshl_add_u64 v[12:13], v[12:13], 0, v[6:7]
	v_and_b32_e32 v6, 0xf8, v144
	v_lshl_add_u64 v[14:15], s[4:5], 0, v[6:7]
	v_lshl_add_u64 v[14:15], v[14:15], 0, s[2:3]
	s_branch .LBB0_648

.LBB0_648:
	s_mul_hi_i32 s2, s26, 0x2ad5802b
	s_lshr_b32 s3, s2, 31
	s_ashr_i32 s2, s2, 10
	s_add_i32 s28, s2, s3
	v_lshl_or_b32 v16, s28, 6, v229
	v_ashrrev_i32_e32 v17, 31, v16
	v_lshl_add_u64 v[16:17], v[16:17], 2, v[2:3]
	global_load_dword v6, v[16:17], off
	s_mul_i32 s2, s28, 0x17e8
	s_sub_i32 s14, s26, s2
	s_ashr_i32 s29, s28, 31
	s_mul_i32 s2, s28, 0x1800
	s_ashr_i32 s15, s14, 31
	s_mul_hi_i32 s3, s28, 0x1800
	s_add_u32 s2, s2, s14
	s_addc_u32 s3, s3, s15
	s_lshl_b64 s[2:3], s[2:3], 9
	s_add_u32 s2, s16, s2
	s_addc_u32 s3, s21, s3
	s_lshl_b64 s[28:29], s[28:29], 16
	v_mov_b32_e32 v9, 0
	v_lshl_add_u64 v[16:17], v[0:1], 0, s[28:29]
	s_mov_b32 s15, -2
	v_mov_b32_e32 v18, 0
	v_mov_b32_e32 v19, v9
	v_mov_b64_e32 v[36:37], s[2:3]
	global_load_dword v11, v[16:17], off
	global_load_dword v38, v[16:17], off offset:256
	global_load_dword v39, v[16:17], off offset:512
	global_load_dword v27, v[16:17], off offset:768
	global_load_dword v46, v[16:17], off offset:1024
	global_load_dword v40, v[16:17], off offset:1280
	global_load_dword v41, v[16:17], off offset:1536
	global_load_dword v47, v[16:17], off offset:1792
	global_load_dword v48, v[16:17], off offset:2048
	global_load_dword v42, v[16:17], off offset:2304
	global_load_dword v43, v[16:17], off offset:2560
	global_load_dword v49, v[16:17], off offset:2816
	global_load_dword v50, v[16:17], off offset:3072
	global_load_dword v44, v[16:17], off offset:3328
	global_load_dwordx4 v[28:31], v[36:37], off
	global_load_dwordx4 v[32:35], v[36:37], off offset:16
	global_load_dword v45, v[16:17], off offset:3584
	global_load_dword v51, v[16:17], off offset:3840
	s_add_u32 s2, s2, 32
	s_addc_u32 s3, s3, 0
	v_lshl_add_u64 v[16:17], v[16:17], 0, s[6:7]
	s_mov_b32 s15, 7
.Lc2_loop:
	v_mov_b64_e32 v[156:157], s[2:3]
	global_load_dword v130, v[16:17], off
	global_load_dword v132, v[16:17], off offset:256
	global_load_dword v133, v[16:17], off offset:512
	global_load_dword v131, v[16:17], off offset:768
	global_load_dword v140, v[16:17], off offset:1024
	global_load_dword v134, v[16:17], off offset:1280
	global_load_dword v135, v[16:17], off offset:1536
	global_load_dword v141, v[16:17], off offset:1792
	global_load_dword v142, v[16:17], off offset:2048
	global_load_dword v136, v[16:17], off offset:2304
	global_load_dword v137, v[16:17], off offset:2560
	global_load_dword v143, v[16:17], off offset:2816
	global_load_dword v146, v[16:17], off offset:3072
	global_load_dword v138, v[16:17], off offset:3328
	global_load_dwordx4 v[148:151], v[156:157], off
	global_load_dwordx4 v[152:155], v[156:157], off offset:16
	global_load_dword v139, v[16:17], off offset:3584
	global_load_dword v147, v[16:17], off offset:3840
	s_add_u32 s2, s2, 32
	s_addc_u32 s3, s3, 0
	v_lshl_add_u64 v[16:17], v[16:17], 0, s[6:7]
	s_waitcnt vmcnt(18)
	v_lshlrev_b32_e32 v52, 16, v28
	v_and_b32_e32 v36, 0xffff0000, v28
	v_lshlrev_b32_e32 v37, 16, v29
	v_and_b32_e32 v53, 0xffff0000, v29
	v_lshlrev_b32_e32 v54, 16, v30
	v_and_b32_e32 v28, 0xffff0000, v30
	v_lshlrev_b32_e32 v29, 16, v31
	v_and_b32_e32 v55, 0xffff0000, v31
	v_fmac_f32_e32 v6, v11, v52
	v_pk_fma_f32 v[18:19], v[38:39], v[36:37], v[18:19]
	v_fmac_f32_e32 v9, v27, v53
	v_lshlrev_b32_e32 v56, 16, v32
	v_and_b32_e32 v30, 0xffff0000, v32
	v_lshlrev_b32_e32 v31, 16, v33
	v_and_b32_e32 v57, 0xffff0000, v33
	v_fmac_f32_e32 v6, v46, v54
	v_pk_fma_f32 v[18:19], v[40:41], v[28:29], v[18:19]
	v_fmac_f32_e32 v9, v47, v55
	v_lshlrev_b32_e32 v58, 16, v34
	v_and_b32_e32 v32, 0xffff0000, v34
	v_lshlrev_b32_e32 v33, 16, v35
	v_and_b32_e32 v34, 0xffff0000, v35
	v_fmac_f32_e32 v6, v48, v56
	v_pk_fma_f32 v[18:19], v[42:43], v[30:31], v[18:19]
	v_fmac_f32_e32 v9, v49, v57
	v_fmac_f32_e32 v6, v50, v58
	v_pk_fma_f32 v[18:19], v[44:45], v[32:33], v[18:19]
	v_fmac_f32_e32 v9, v51, v34
	s_cmp_eq_u32 s15, 0
	s_cbranch_scc1 .Lc2_tail
	s_sub_u32 s15, s15, 1
	v_mov_b64_e32 v[36:37], s[2:3]
	global_load_dword v11, v[16:17], off
	global_load_dword v38, v[16:17], off offset:256
	global_load_dword v39, v[16:17], off offset:512
	global_load_dword v27, v[16:17], off offset:768
	global_load_dword v46, v[16:17], off offset:1024
	global_load_dword v40, v[16:17], off offset:1280
	global_load_dword v41, v[16:17], off offset:1536
	global_load_dword v47, v[16:17], off offset:1792
	global_load_dword v48, v[16:17], off offset:2048
	global_load_dword v42, v[16:17], off offset:2304
	global_load_dword v43, v[16:17], off offset:2560
	global_load_dword v49, v[16:17], off offset:2816
	global_load_dword v50, v[16:17], off offset:3072
	global_load_dword v44, v[16:17], off offset:3328
	global_load_dwordx4 v[28:31], v[36:37], off
	global_load_dwordx4 v[32:35], v[36:37], off offset:16
	global_load_dword v45, v[16:17], off offset:3584
	global_load_dword v51, v[16:17], off offset:3840
	s_add_u32 s2, s2, 32
	s_addc_u32 s3, s3, 0
	v_lshl_add_u64 v[16:17], v[16:17], 0, s[6:7]
	s_waitcnt vmcnt(18)
	v_lshlrev_b32_e32 v158, 16, v148
	v_and_b32_e32 v156, 0xffff0000, v148
	v_lshlrev_b32_e32 v157, 16, v149
	v_and_b32_e32 v159, 0xffff0000, v149
	v_lshlrev_b32_e32 v160, 16, v150
	v_and_b32_e32 v148, 0xffff0000, v150
	v_lshlrev_b32_e32 v149, 16, v151
	v_and_b32_e32 v161, 0xffff0000, v151
	v_fmac_f32_e32 v6, v130, v158
	v_pk_fma_f32 v[18:19], v[132:133], v[156:157], v[18:19]
	v_fmac_f32_e32 v9, v131, v159
	v_lshlrev_b32_e32 v162, 16, v152
	v_and_b32_e32 v150, 0xffff0000, v152
	v_lshlrev_b32_e32 v151, 16, v153
	v_and_b32_e32 v163, 0xffff0000, v153
	v_fmac_f32_e32 v6, v140, v160
	v_pk_fma_f32 v[18:19], v[134:135], v[148:149], v[18:19]
	v_fmac_f32_e32 v9, v141, v161
	v_lshlrev_b32_e32 v164, 16, v154
	v_and_b32_e32 v152, 0xffff0000, v154
	v_lshlrev_b32_e32 v153, 16, v155
	v_and_b32_e32 v154, 0xffff0000, v155
	v_fmac_f32_e32 v6, v142, v162
	v_pk_fma_f32 v[18:19], v[136:137], v[150:151], v[18:19]
	v_fmac_f32_e32 v9, v143, v163
	v_fmac_f32_e32 v6, v146, v164
	v_pk_fma_f32 v[18:19], v[138:139], v[152:153], v[18:19]
	v_fmac_f32_e32 v9, v147, v154
	s_branch .Lc2_loop
.Lc2_tail:
	s_waitcnt vmcnt(0)
	v_lshlrev_b32_e32 v158, 16, v148
	v_and_b32_e32 v156, 0xffff0000, v148
	v_lshlrev_b32_e32 v157, 16, v149
	v_and_b32_e32 v159, 0xffff0000, v149
	v_lshlrev_b32_e32 v160, 16, v150
	v_and_b32_e32 v148, 0xffff0000, v150
	v_lshlrev_b32_e32 v149, 16, v151
	v_and_b32_e32 v161, 0xffff0000, v151
	v_fmac_f32_e32 v6, v130, v158
	v_pk_fma_f32 v[18:19], v[132:133], v[156:157], v[18:19]
	v_fmac_f32_e32 v9, v131, v159
	v_lshlrev_b32_e32 v162, 16, v152
	v_and_b32_e32 v150, 0xffff0000, v152
	v_lshlrev_b32_e32 v151, 16, v153
	v_and_b32_e32 v163, 0xffff0000, v153
	v_fmac_f32_e32 v6, v140, v160
	v_pk_fma_f32 v[18:19], v[134:135], v[148:149], v[18:19]
	v_fmac_f32_e32 v9, v141, v161
	v_lshlrev_b32_e32 v164, 16, v154
	v_and_b32_e32 v152, 0xffff0000, v154
	v_lshlrev_b32_e32 v153, 16, v155
	v_and_b32_e32 v154, 0xffff0000, v155
	v_fmac_f32_e32 v6, v142, v162
	v_pk_fma_f32 v[18:19], v[136:137], v[150:151], v[18:19]
	v_fmac_f32_e32 v9, v143, v163
	v_fmac_f32_e32 v6, v146, v164
	v_pk_fma_f32 v[18:19], v[138:139], v[152:153], v[18:19]
	v_fmac_f32_e32 v9, v147, v154
	s_mul_i32 s2, s14, 0xffff8081
	s_lshr_b32 s2, s2, 16
	s_add_i32 s2, s2, s14
	s_sext_i32_i16 s3, s2
	s_ashr_i32 s3, s3, 7
	s_bfe_u32 s2, s2, 0x1000f
	s_add_i32 s15, s3, s2
	s_mul_i32 s2, s15, 0xff
	s_sub_i32 s2, s14, s2
	v_add_f32_e32 v6, v6, v18
	v_add_f32_e32 v9, v19, v9
	s_add_i32 s14, s26, 0x17e7
	s_sext_i32_i16 s27, s2
	v_add_f32_e32 v11, v6, v9
	s_mov_b64 s[2:3], -1
	s_cmpk_gt_u32 s14, 0x2fce
	s_sext_i32_i16 s14, s15
	s_cbranch_scc0 .LBB0_654
	s_ashr_i32 s15, s14, 31
	s_lshl_b64 s[2:3], s[14:15], 15
	s_add_u32 s2, s22, s2
	s_addc_u32 s3, s23, s3
	s_lshr_b32 s15, s27, 1
	s_and_b32 s15, s15, 4
	s_and_b32 s28, s27, 3
	v_bfe_u32 v6, v11, 16, 1
	s_or_b32 s15, s28, s15
	s_ashr_i32 s28, s27, 5
	s_lshr_b32 s30, s27, 3
	v_add3_u32 v9, v11, v6, s17
	s_ashr_i32 s29, s28, 31
	v_and_or_b32 v6, s30, 2, v230
	s_lshl_b32 s30, s27, 3
	s_and_b32 s30, s30, 32
	s_lshl_b64 s[28:29], s[28:29], 12
	v_lshlrev_b32_e32 v6, 6, v6
	s_add_u32 s28, s2, s28
	v_or3_b32 v6, v6, s30, v172
	s_addc_u32 s29, s3, s29
	s_lshl_b32 s15, s15, 1
	v_lshl_or_b32 v6, v6, 4, s15
	s_and_b32 s15, s27, 0xffff
	v_lshl_add_u64 v[16:17], s[28:29], 0, v[6:7]
	s_cmpk_lg_i32 s15, 0xfe
	flat_store_short_d16_hi v[16:17], v9
	s_cbranch_scc1 .LBB0_653
	v_mov_b32_e32 v9, v7
	v_lshl_add_u64 v[16:17], s[2:3], 0, v[8:9]
	flat_store_short v[16:17], v7

.LBB0_719:
	s_or_b64 exec, exec, s[0:1]
	s_waitcnt lgkmcnt(0)
	v_mov_b32_e32 v0, 0
	s_barrier
	v_mov_b32_e32 v178, s44
	v_mov_b32_e32 v179, s45
	s_add_u32 s60, s44, 0x3308040
	s_addc_u32 s61, s45, 0
	s_lshr_b32 s53, s84, 8
	s_bfe_u32 s55, s84, 0x20006
	s_cmpk_gt_u32 s84, 0xff
	s_cselect_b64 s[0:1], -1, 0
	s_waitcnt vmcnt(0)
	v_add_co_u32_e32 v0, vcc, 0x3308000, v178
	s_nop 1
	v_addc_co_u32_e32 v1, vcc, 0, v179, vcc
	flat_load_dword v0, v[0:1] offset:1024
	v_mov_b32_e32 v1, 0x3308000
	global_load_dwordx2 v[180:181], v1, s[44:45] offset:64
	global_load_dwordx2 v[182:183], v1, s[44:45] offset:96
	s_waitcnt vmcnt(0) lgkmcnt(0)
	v_readfirstlane_b32 s2, v0
	v_cndmask_b32_e64 v0, 0, 1, s[0:1]
	v_cmp_ne_u32_e64 s[0:1], 1, v0
	s_cmp_eq_u32 s2, 0
	s_nop 0
	v_writelane_b32 v255, s0, 1
	s_nop 1
	v_writelane_b32 v255, s1, 2
	s_cbranch_scc1 .LBB0_723
	s_and_b64 vcc, exec, s[0:1]
	s_cbranch_vccz .LBB0_724
	s_cmpk_eq_i32 s46, 0x100
	s_mov_b64 s[0:1], -1
	s_cbranch_scc0 .LBB0_725

.LBB0_1357:
	s_or_b64 exec, exec, s[0:1]
	v_mov_b32_e32 v17, 0
	s_waitcnt lgkmcnt(0)
	s_barrier
	v_mov_b32_e32 v0, s44
	v_mov_b32_e32 v1, s45
	v_cndmask_b32_e64 v2, 0, 1, s[58:59]
	v_cmp_ne_u32_e64 s[0:1], 1, v2
	s_andn2_b64 vcc, exec, s[58:59]
	s_waitcnt vmcnt(0)
	v_readfirstlane_b32 s58, v0
	v_writelane_b32 v255, s0, 5
	v_readfirstlane_b32 s59, v1
	s_nop 0
	v_writelane_b32 v255, s1, 6
	s_cbranch_vccnz .LBB0_1360
	v_mov_b32_e32 v0, 0x3308000
	global_load_dwordx2 v[0:1], v0, s[44:45] offset:168
	s_add_u32 s66, s58, 0x3400000
	s_addc_u32 s67, s59, 0
	v_lshlrev_b32_e32 v16, 4, v176
	v_mbcnt_hi_u32_b32 v6, -1, v228
	s_add_u32 s89, s58, 0xb000000
	s_mov_b64 s[2:3], 0xd000000
	v_lshlrev_b32_e32 v4, 4, v173
	v_lshl_add_u64 v[2:3], s[58:59], 0, v[16:17]
	v_and_b32_e32 v7, 64, v6
	s_addc_u32 s90, s59, 0
	v_and_b32_e32 v131, 48, v4
	v_xor_b32_e32 v4, 4, v6
	v_lshl_add_u64 v[18:19], v[2:3], 0, s[2:3]
	v_add_u32_e32 v2, 64, v7
	s_add_u32 s91, s58, 0x1d000000
	v_lshlrev_b32_e32 v5, 17, v174
	v_lshlrev_b32_e32 v16, 5, v176
	v_cmp_lt_i32_e32 vcc, v4, v2
	s_addc_u32 s92, s59, 0
	s_lshl_b32 s2, s18, 6
	s_lshl_b32 s3, s85, 3
	v_cndmask_b32_e32 v2, v6, v4, vcc
	s_add_i32 s95, s2, s3
	s_mov_b64 s[6:7], 0x1b000000
	v_lshlrev_b32_e32 v132, 2, v2
	v_or_b32_e32 v2, s95, v174
	v_cmp_gt_u32_e64 s[0:1], 4, v176
	v_lshlrev_b32_e32 v128, 8, v176
	s_movk_i32 s53, 0x1600
	s_mov_b32 s55, 0xffff0000
	v_mov_b32_e32 v129, 0x358637bd
	s_mov_b32 s87, 0xf800000
	v_mov_b32_e32 v130, 0x260
	s_movk_i32 s88, 0x7fff
	s_lshl_b32 s93, s46, 6
	s_lshl_b32 s94, s46, 20
	v_lshlrev_b32_e32 v133, 14, v2
	s_mov_b32 s96, s52
	s_waitcnt vmcnt(0)
	v_lshl_add_u64 v[20:21], v[0:1], 0, v[16:17]
	v_and_b32_e32 v16, 0x60000, v5
	v_lshl_add_u64 v[0:1], s[58:59], 0, v[16:17]
	v_lshl_add_u64 v[22:23], v[0:1], 0, s[6:7]

.LBB0_1419:
	s_or_b64 exec, exec, s[0:1]
	v_mov_b32_e32 v2, 0x3308000
	s_waitcnt lgkmcnt(0)
	s_barrier
	v_mov_b32_e32 v4, 0
	global_load_dwordx2 v[146:147], v2, s[44:45] offset:192
	v_mov_b32_e32 v0, s44
	v_mov_b32_e32 v1, s45
	s_nop 0
	v_add_co_u32_e32 v2, vcc, 0x3308000, v0
	s_nop 1
	v_addc_co_u32_e32 v3, vcc, 0, v1, vcc
	flat_load_dword v5, v[2:3] offset:1024
	global_load_dwordx2 v[144:145], v4, s[60:61]
	v_readfirstlane_b32 s12, v0
	v_readfirstlane_b32 s13, v1
	s_waitcnt vmcnt(0) lgkmcnt(0)
	v_readfirstlane_b32 s0, v5
	s_cmp_eq_u32 s0, 0
	s_cbranch_scc1 .LBB0_1423
	v_readlane_b32 s0, v255, 1
	v_readlane_b32 s1, v255, 2
	s_and_b64 vcc, exec, s[0:1]
	s_cbranch_vccz .LBB0_1424
	s_cmpk_eq_i32 s46, 0x100
	s_mov_b64 s[0:1], -1
	s_cbranch_scc0 .LBB0_1425
